# weight conversion: hand-written tile loop with 6 tiles in flight per iteration (was 1)
# speedup vs baseline: 1.0021x; 1.0021x over previous
; __device__ __forceinline__ int fresh_bid() { int t; asm volatile("s_mov_b32 %0, %1" : "=s"(t) : "s"(blockIdx.x)); return t; }
; __device__ __forceinline__ void phase_convert(const Ctx& a, int l, LAS unsigned char* lds) {
;     ...
;     for (int j = 0; j < 10; ++j) {
;         CJob c = get_job(j, a, l);
;         const int nkt = c.K / 64, nnt = c.Ntot / 64, ntile = nkt * nnt;
;         int first = (int)((fresh_bid() + gridDim.x - (base % gridDim.x)) % gridDim.x);
;         float pv[8];
;     ...
;         if (first < ntile) CV_LOAD(first);
;         for (int i = first; i < ntile; i += gridDim.x) {
.LBB0_717:
	s_mov_b32 s30, s2
	s_load_dword s9, s[74:75], 0x0
	s_mul_i32 s52, s26, s51
	v_cvt_f32_u32_e32 v22, s51
	s_waitcnt lgkmcnt(0)
	v_cvt_f32_u32_e32 v21, s9
	s_sub_i32 s26, 0, s9
	v_rcp_iflag_f32_e32 v21, v21
	s_nop 0
	v_mul_f32_e32 v21, 0x4f7ffffe, v21
	v_cvt_u32_f32_e32 v23, v21
	v_rcp_iflag_f32_e32 v21, v22
	v_readfirstlane_b32 s42, v23
	s_mul_i32 s26, s26, s42
	s_mul_hi_u32 s26, s42, s26
	s_add_i32 s42, s42, s26
	s_mul_hi_u32 s26, s48, s42
	s_mul_i32 s26, s26, s9
	s_sub_i32 s26, s48, s26
	s_sub_i32 s43, s26, s9
	s_cmp_ge_u32 s26, s9
	s_cselect_b32 s26, s43, s26
	s_sub_i32 s43, s26, s9
	s_cmp_ge_u32 s26, s9
	s_cselect_b32 s26, s43, s26
	s_add_i32 s30, s9, s30
	s_sub_i32 s26, s30, s26
	s_mul_hi_u32 s30, s26, s42
	s_mul_i32 s30, s30, s9
	s_sub_i32 s26, s26, s30
	s_sub_i32 s30, s26, s9
	s_cmp_ge_u32 s26, s9
	s_cselect_b32 s26, s30, s26
	s_sub_i32 s30, s26, s9
	s_cmp_ge_u32 s26, s9
	s_cselect_b32 s53, s30, s26
	s_cmp_lt_i32 s53, s52
	s_cselect_b64 s[44:45], -1, 0
	s_cmp_ge_i32 s53, s52
	s_cbranch_scc1 .LBB0_693
	s_waitcnt vmcnt(0) lgkmcnt(0)
	v_mul_f32_e32 v21, 0x4f7ffffe, v21
	v_cvt_u32_f32_e32 v21, v21
	s_sub_i32 s26, 0, s51
	v_readfirstlane_b32 s44, v21
	v_readfirstlane_b32 s56, v14
	v_readfirstlane_b32 s57, v15
	v_readfirstlane_b32 s58, v16
	v_readfirstlane_b32 s59, v17
	s_xor_b64 s[42:43], s[36:37], -1
	v_cmp_ne_u64_e64 s[36:37], 0, v[16:17]
	s_nop 3
	s_mul_i32 s26, s26, s44
	s_mul_hi_u32 s26, s44, s26
	s_add_i32 s54, s44, s26
	s_lshl_b64 s[44:45], s[40:41], 1
	s_add_u32 s38, s38, s44
	s_addc_u32 s39, s39, s45
	s_lshl_b64 s[40:41], s[0:1], 5
	v_lshlrev_b32_e32 v141, 2, v2
	v_add_u32_e32 v32, 0x10400, v20
	v_mov_b32_e32 v42, 1.0
	v_mov_b32_e32 v43, 1.0
	v_mov_b32_e32 v44, 1.0
	v_mov_b32_e32 v45, 1.0
	v_mov_b32_e32 v46, 1.0
	v_mov_b32_e32 v47, 1.0
	v_mov_b32_e32 v48, 1.0
	v_mov_b32_e32 v49, 1.0
	v_mov_b32_e32 v58, 1.0
	v_mov_b32_e32 v59, 1.0
	v_mov_b32_e32 v60, 1.0
	v_mov_b32_e32 v61, 1.0
	v_mov_b32_e32 v62, 1.0
	v_mov_b32_e32 v63, 1.0
	v_mov_b32_e32 v64, 1.0
	v_mov_b32_e32 v65, 1.0
	v_mov_b32_e32 v74, 1.0
	v_mov_b32_e32 v75, 1.0
	v_mov_b32_e32 v76, 1.0
	v_mov_b32_e32 v77, 1.0
	v_mov_b32_e32 v78, 1.0
	v_mov_b32_e32 v79, 1.0
	v_mov_b32_e32 v80, 1.0
	v_mov_b32_e32 v81, 1.0
	v_mov_b32_e32 v90, 1.0
	v_mov_b32_e32 v91, 1.0
	v_mov_b32_e32 v92, 1.0
	v_mov_b32_e32 v93, 1.0
	v_mov_b32_e32 v94, 1.0
	v_mov_b32_e32 v95, 1.0
	v_mov_b32_e32 v96, 1.0
	v_mov_b32_e32 v97, 1.0
	v_mov_b32_e32 v106, 1.0
	v_mov_b32_e32 v107, 1.0
	v_mov_b32_e32 v108, 1.0
	v_mov_b32_e32 v109, 1.0
	v_mov_b32_e32 v110, 1.0
	v_mov_b32_e32 v111, 1.0
	v_mov_b32_e32 v112, 1.0
	v_mov_b32_e32 v113, 1.0
	v_mov_b32_e32 v122, 1.0
	v_mov_b32_e32 v123, 1.0
	v_mov_b32_e32 v124, 1.0
	v_mov_b32_e32 v125, 1.0
	v_mov_b32_e32 v126, 1.0
	v_mov_b32_e32 v127, 1.0
	v_mov_b32_e32 v128, 1.0
	v_mov_b32_e32 v129, 1.0
	s_mov_b32 s60, 0
	s_mov_b32 s30, s53
	s_cmp_ge_i32 s30, s52
	s_cbranch_scc1 .Lcv_isd_a
	s_mul_hi_u32 s26, s30, s54
	s_mul_i32 s55, s26, s51
	s_sub_i32 s55, s30, s55
	s_sub_i32 s61, s55, s51
	s_add_i32 s62, s26, 1
	s_cmp_ge_u32 s55, s51
	s_cselect_b32 s26, s62, s26
	s_cselect_b32 s55, s61, s55
	s_sub_i32 s61, s55, s51
	s_add_i32 s62, s26, 1
	s_cmp_ge_u32 s55, s51
	s_cselect_b32 s26, s62, s26
	s_cselect_b32 s55, s61, s55
	s_lshl_b32 s61, s26, 6
	s_lshl_b32 s62, s55, 6
	v_add_u32_e32 v130, s62, v1
	s_add_i32 s44, s50, -1
	v_min_u32_e32 v136, s44, v130
	v_add_u32_e32 v137, s61, v2
	v_mad_u32_u24 v136, v137, s0, v136
	v_lshlrev_b32_e32 v136, 2, v136
	s_mov_b64 s[44:45], s[56:57]
	global_load_dword v34, v136, s[44:45] nt
	s_add_u32 s44, s44, s40
	s_addc_u32 s45, s45, s41
	global_load_dword v35, v136, s[44:45] nt
	s_add_u32 s44, s44, s40
	s_addc_u32 s45, s45, s41
	global_load_dword v36, v136, s[44:45] nt
	s_add_u32 s44, s44, s40
	s_addc_u32 s45, s45, s41
	global_load_dword v37, v136, s[44:45] nt
	s_add_u32 s44, s44, s40
	s_addc_u32 s45, s45, s41
	global_load_dword v38, v136, s[44:45] nt
	s_add_u32 s44, s44, s40
	s_addc_u32 s45, s45, s41
	global_load_dword v39, v136, s[44:45] nt
	s_add_u32 s44, s44, s40
	s_addc_u32 s45, s45, s41
	global_load_dword v40, v136, s[44:45] nt
	s_add_u32 s44, s44, s40
	s_addc_u32 s45, s45, s41
	global_load_dword v41, v136, s[44:45] nt
	s_cmp_eq_u64 s[36:37], 0
	s_cbranch_scc1 .Lcv_ng_a_0
	s_lshl_b32 s61, s61, 2
	s_add_u32 s44, s58, s61
	s_addc_u32 s45, s59, 0
	global_load_dword v42, v141, s[44:45] offset:0
	global_load_dword v43, v141, s[44:45] offset:32
	global_load_dword v44, v141, s[44:45] offset:64
	global_load_dword v45, v141, s[44:45] offset:96
	global_load_dword v46, v141, s[44:45] offset:128
	global_load_dword v47, v141, s[44:45] offset:160
	global_load_dword v48, v141, s[44:45] offset:192
	global_load_dword v49, v141, s[44:45] offset:224
; __device__ __forceinline__ int fresh_bid() { int t; asm volatile("s_mov_b32 %0, %1" : "=s"(t) : "s"(blockIdx.x)); return t; }
; __device__ __forceinline__ void phase_convert(const Ctx& a, int l, LAS unsigned char* lds) {
;     ...
;         int first = (int)((fresh_bid() + gridDim.x - (base % gridDim.x)) % gridDim.x);
;         float pv[8];
;     ...
;         if (first < ntile) CV_LOAD(first);
;         for (int i = first; i < ntile; i += gridDim.x) {
;             const int kt = i / nnt, ntl = i % nnt, k0 = kt * 64, n0 = ntl * 64;
; #pragma unroll
;             for (int it = 0; it < 8; ++it) tile[((tid >> 6) + it * 8) * 65 + (tid & 63)] = pv[it];
;             __syncthreads();
;             if (i + (int)gridDim.x < ntile) CV_LOAD(i + gridDim.x);
.Lcv_ng_a_0:
	s_add_i32 s60, s60, 1
	s_add_i32 s30, s30, s9
	s_cmp_ge_i32 s30, s52
	s_cbranch_scc1 .Lcv_isd_a
	s_mul_hi_u32 s26, s30, s54
	s_mul_i32 s55, s26, s51
	s_sub_i32 s55, s30, s55
	s_sub_i32 s61, s55, s51
	s_add_i32 s62, s26, 1
	s_cmp_ge_u32 s55, s51
	s_cselect_b32 s26, s62, s26
	s_cselect_b32 s55, s61, s55
	s_sub_i32 s61, s55, s51
	s_add_i32 s62, s26, 1
	s_cmp_ge_u32 s55, s51
	s_cselect_b32 s26, s62, s26
	s_cselect_b32 s55, s61, s55
	s_lshl_b32 s61, s26, 6
	s_lshl_b32 s62, s55, 6
	v_add_u32_e32 v131, s62, v1
	s_add_i32 s44, s50, -1
	v_min_u32_e32 v136, s44, v131
	v_add_u32_e32 v137, s61, v2
	v_mad_u32_u24 v136, v137, s0, v136
	v_lshlrev_b32_e32 v136, 2, v136
	s_mov_b64 s[44:45], s[56:57]
	global_load_dword v50, v136, s[44:45] nt
	s_add_u32 s44, s44, s40
	s_addc_u32 s45, s45, s41
	global_load_dword v51, v136, s[44:45] nt
	s_add_u32 s44, s44, s40
	s_addc_u32 s45, s45, s41
	global_load_dword v52, v136, s[44:45] nt
	s_add_u32 s44, s44, s40
	s_addc_u32 s45, s45, s41
	global_load_dword v53, v136, s[44:45] nt
	s_add_u32 s44, s44, s40
	s_addc_u32 s45, s45, s41
	global_load_dword v54, v136, s[44:45] nt
	s_add_u32 s44, s44, s40
	s_addc_u32 s45, s45, s41
	global_load_dword v55, v136, s[44:45] nt
	s_add_u32 s44, s44, s40
	s_addc_u32 s45, s45, s41
	global_load_dword v56, v136, s[44:45] nt
	s_add_u32 s44, s44, s40
	s_addc_u32 s45, s45, s41
	global_load_dword v57, v136, s[44:45] nt
	s_cmp_eq_u64 s[36:37], 0
	s_cbranch_scc1 .Lcv_ng_a_1
	s_lshl_b32 s61, s61, 2
	s_add_u32 s44, s58, s61
	s_addc_u32 s45, s59, 0
	global_load_dword v58, v141, s[44:45] offset:0
	global_load_dword v59, v141, s[44:45] offset:32
	global_load_dword v60, v141, s[44:45] offset:64
	global_load_dword v61, v141, s[44:45] offset:96
	global_load_dword v62, v141, s[44:45] offset:128
	global_load_dword v63, v141, s[44:45] offset:160
	global_load_dword v64, v141, s[44:45] offset:192
	global_load_dword v65, v141, s[44:45] offset:224
.Lcv_ng_a_1:
	s_add_i32 s60, s60, 1
	s_add_i32 s30, s30, s9
	s_cmp_ge_i32 s30, s52
	s_cbranch_scc1 .Lcv_isd_a
	s_mul_hi_u32 s26, s30, s54
	s_mul_i32 s55, s26, s51
	s_sub_i32 s55, s30, s55
	s_sub_i32 s61, s55, s51
	s_add_i32 s62, s26, 1
	s_cmp_ge_u32 s55, s51
	s_cselect_b32 s26, s62, s26
	s_cselect_b32 s55, s61, s55
	s_sub_i32 s61, s55, s51
	s_add_i32 s62, s26, 1
	s_cmp_ge_u32 s55, s51
	s_cselect_b32 s26, s62, s26
	s_cselect_b32 s55, s61, s55
	s_lshl_b32 s61, s26, 6
	s_lshl_b32 s62, s55, 6
	v_add_u32_e32 v132, s62, v1
	s_add_i32 s44, s50, -1
	v_min_u32_e32 v136, s44, v132
	v_add_u32_e32 v137, s61, v2
	v_mad_u32_u24 v136, v137, s0, v136
	v_lshlrev_b32_e32 v136, 2, v136
	s_mov_b64 s[44:45], s[56:57]
	global_load_dword v66, v136, s[44:45] nt
	s_add_u32 s44, s44, s40
	s_addc_u32 s45, s45, s41
	global_load_dword v67, v136, s[44:45] nt
	s_add_u32 s44, s44, s40
	s_addc_u32 s45, s45, s41
	global_load_dword v68, v136, s[44:45] nt
	s_add_u32 s44, s44, s40
	s_addc_u32 s45, s45, s41
	global_load_dword v69, v136, s[44:45] nt
	s_add_u32 s44, s44, s40
	s_addc_u32 s45, s45, s41
	global_load_dword v70, v136, s[44:45] nt
	s_add_u32 s44, s44, s40
	s_addc_u32 s45, s45, s41
	global_load_dword v71, v136, s[44:45] nt
	s_add_u32 s44, s44, s40
	s_addc_u32 s45, s45, s41
	global_load_dword v72, v136, s[44:45] nt
	s_add_u32 s44, s44, s40
	s_addc_u32 s45, s45, s41
	global_load_dword v73, v136, s[44:45] nt
	s_cmp_eq_u64 s[36:37], 0
	s_cbranch_scc1 .Lcv_ng_a_2
	s_lshl_b32 s61, s61, 2
	s_add_u32 s44, s58, s61
	s_addc_u32 s45, s59, 0
	global_load_dword v74, v141, s[44:45] offset:0
	global_load_dword v75, v141, s[44:45] offset:32
	global_load_dword v76, v141, s[44:45] offset:64
	global_load_dword v77, v141, s[44:45] offset:96
	global_load_dword v78, v141, s[44:45] offset:128
	global_load_dword v79, v141, s[44:45] offset:160
	global_load_dword v80, v141, s[44:45] offset:192
	global_load_dword v81, v141, s[44:45] offset:224
.Lcv_ng_a_2:
	s_add_i32 s60, s60, 1
	s_add_i32 s30, s30, s9
	s_cmp_ge_i32 s30, s52
	s_cbranch_scc1 .Lcv_isd_a
	s_mul_hi_u32 s26, s30, s54
	s_mul_i32 s55, s26, s51
	s_sub_i32 s55, s30, s55
	s_sub_i32 s61, s55, s51
	s_add_i32 s62, s26, 1
	s_cmp_ge_u32 s55, s51
	s_cselect_b32 s26, s62, s26
	s_cselect_b32 s55, s61, s55
	s_sub_i32 s61, s55, s51
	s_add_i32 s62, s26, 1
	s_cmp_ge_u32 s55, s51
	s_cselect_b32 s26, s62, s26
	s_cselect_b32 s55, s61, s55
	s_lshl_b32 s61, s26, 6
	s_lshl_b32 s62, s55, 6
	v_add_u32_e32 v133, s62, v1
	s_add_i32 s44, s50, -1
	v_min_u32_e32 v136, s44, v133
	v_add_u32_e32 v137, s61, v2
	v_mad_u32_u24 v136, v137, s0, v136
	v_lshlrev_b32_e32 v136, 2, v136
	s_mov_b64 s[44:45], s[56:57]
	global_load_dword v82, v136, s[44:45] nt
	s_add_u32 s44, s44, s40
	s_addc_u32 s45, s45, s41
	global_load_dword v83, v136, s[44:45] nt
	s_add_u32 s44, s44, s40
	s_addc_u32 s45, s45, s41
	global_load_dword v84, v136, s[44:45] nt
	s_add_u32 s44, s44, s40
	s_addc_u32 s45, s45, s41
	global_load_dword v85, v136, s[44:45] nt
	s_add_u32 s44, s44, s40
	s_addc_u32 s45, s45, s41
	global_load_dword v86, v136, s[44:45] nt
	s_add_u32 s44, s44, s40
	s_addc_u32 s45, s45, s41
	global_load_dword v87, v136, s[44:45] nt
	s_add_u32 s44, s44, s40
	s_addc_u32 s45, s45, s41
	global_load_dword v88, v136, s[44:45] nt
	s_add_u32 s44, s44, s40
	s_addc_u32 s45, s45, s41
	global_load_dword v89, v136, s[44:45] nt
	s_cmp_eq_u64 s[36:37], 0
	s_cbranch_scc1 .Lcv_ng_a_3
	s_lshl_b32 s61, s61, 2
	s_add_u32 s44, s58, s61
	s_addc_u32 s45, s59, 0
	global_load_dword v90, v141, s[44:45] offset:0
	global_load_dword v91, v141, s[44:45] offset:32
	global_load_dword v92, v141, s[44:45] offset:64
	global_load_dword v93, v141, s[44:45] offset:96
	global_load_dword v94, v141, s[44:45] offset:128
	global_load_dword v95, v141, s[44:45] offset:160
	global_load_dword v96, v141, s[44:45] offset:192
	global_load_dword v97, v141, s[44:45] offset:224
; __device__ __forceinline__ int fresh_bid() { int t; asm volatile("s_mov_b32 %0, %1" : "=s"(t) : "s"(blockIdx.x)); return t; }
; __device__ __forceinline__ void phase_convert(const Ctx& a, int l, LAS unsigned char* lds) {
;     ...
;         int first = (int)((fresh_bid() + gridDim.x - (base % gridDim.x)) % gridDim.x);
;         float pv[8];
;     ...
;         if (first < ntile) CV_LOAD(first);
;         for (int i = first; i < ntile; i += gridDim.x) {
;             const int kt = i / nnt, ntl = i % nnt, k0 = kt * 64, n0 = ntl * 64;
; #pragma unroll
;             for (int it = 0; it < 8; ++it) tile[((tid >> 6) + it * 8) * 65 + (tid & 63)] = pv[it];
;             __syncthreads();
;             if (i + (int)gridDim.x < ntile) CV_LOAD(i + gridDim.x);
.Lcv_ng_a_3:
	s_add_i32 s60, s60, 1
	s_add_i32 s30, s30, s9
	s_cmp_ge_i32 s30, s52
	s_cbranch_scc1 .Lcv_isd_a
	s_mul_hi_u32 s26, s30, s54
	s_mul_i32 s55, s26, s51
	s_sub_i32 s55, s30, s55
	s_sub_i32 s61, s55, s51
	s_add_i32 s62, s26, 1
	s_cmp_ge_u32 s55, s51
	s_cselect_b32 s26, s62, s26
	s_cselect_b32 s55, s61, s55
	s_sub_i32 s61, s55, s51
	s_add_i32 s62, s26, 1
	s_cmp_ge_u32 s55, s51
	s_cselect_b32 s26, s62, s26
	s_cselect_b32 s55, s61, s55
	s_lshl_b32 s61, s26, 6
	s_lshl_b32 s62, s55, 6
	v_add_u32_e32 v134, s62, v1
	s_add_i32 s44, s50, -1
	v_min_u32_e32 v136, s44, v134
	v_add_u32_e32 v137, s61, v2
	v_mad_u32_u24 v136, v137, s0, v136
	v_lshlrev_b32_e32 v136, 2, v136
	s_mov_b64 s[44:45], s[56:57]
	global_load_dword v98, v136, s[44:45] nt
	s_add_u32 s44, s44, s40
	s_addc_u32 s45, s45, s41
	global_load_dword v99, v136, s[44:45] nt
	s_add_u32 s44, s44, s40
	s_addc_u32 s45, s45, s41
	global_load_dword v100, v136, s[44:45] nt
	s_add_u32 s44, s44, s40
	s_addc_u32 s45, s45, s41
	global_load_dword v101, v136, s[44:45] nt
	s_add_u32 s44, s44, s40
	s_addc_u32 s45, s45, s41
	global_load_dword v102, v136, s[44:45] nt
	s_add_u32 s44, s44, s40
	s_addc_u32 s45, s45, s41
	global_load_dword v103, v136, s[44:45] nt
	s_add_u32 s44, s44, s40
	s_addc_u32 s45, s45, s41
	global_load_dword v104, v136, s[44:45] nt
	s_add_u32 s44, s44, s40
	s_addc_u32 s45, s45, s41
	global_load_dword v105, v136, s[44:45] nt
	s_cmp_eq_u64 s[36:37], 0
	s_cbranch_scc1 .Lcv_ng_a_4
	s_lshl_b32 s61, s61, 2
	s_add_u32 s44, s58, s61
	s_addc_u32 s45, s59, 0
	global_load_dword v106, v141, s[44:45] offset:0
	global_load_dword v107, v141, s[44:45] offset:32
	global_load_dword v108, v141, s[44:45] offset:64
	global_load_dword v109, v141, s[44:45] offset:96
	global_load_dword v110, v141, s[44:45] offset:128
	global_load_dword v111, v141, s[44:45] offset:160
	global_load_dword v112, v141, s[44:45] offset:192
	global_load_dword v113, v141, s[44:45] offset:224
.Lcv_ng_a_4:
	s_add_i32 s60, s60, 1
	s_add_i32 s30, s30, s9
	s_cmp_ge_i32 s30, s52
	s_cbranch_scc1 .Lcv_isd_a
	s_mul_hi_u32 s26, s30, s54
	s_mul_i32 s55, s26, s51
	s_sub_i32 s55, s30, s55
	s_sub_i32 s61, s55, s51
	s_add_i32 s62, s26, 1
	s_cmp_ge_u32 s55, s51
	s_cselect_b32 s26, s62, s26
	s_cselect_b32 s55, s61, s55
	s_sub_i32 s61, s55, s51
	s_add_i32 s62, s26, 1
	s_cmp_ge_u32 s55, s51
	s_cselect_b32 s26, s62, s26
	s_cselect_b32 s55, s61, s55
	s_lshl_b32 s61, s26, 6
	s_lshl_b32 s62, s55, 6
	v_add_u32_e32 v135, s62, v1
	s_add_i32 s44, s50, -1
	v_min_u32_e32 v136, s44, v135
	v_add_u32_e32 v137, s61, v2
	v_mad_u32_u24 v136, v137, s0, v136
	v_lshlrev_b32_e32 v136, 2, v136
	s_mov_b64 s[44:45], s[56:57]
	global_load_dword v114, v136, s[44:45] nt
	s_add_u32 s44, s44, s40
	s_addc_u32 s45, s45, s41
	global_load_dword v115, v136, s[44:45] nt
	s_add_u32 s44, s44, s40
	s_addc_u32 s45, s45, s41
	global_load_dword v116, v136, s[44:45] nt
	s_add_u32 s44, s44, s40
	s_addc_u32 s45, s45, s41
	global_load_dword v117, v136, s[44:45] nt
	s_add_u32 s44, s44, s40
	s_addc_u32 s45, s45, s41
	global_load_dword v118, v136, s[44:45] nt
	s_add_u32 s44, s44, s40
	s_addc_u32 s45, s45, s41
	global_load_dword v119, v136, s[44:45] nt
	s_add_u32 s44, s44, s40
	s_addc_u32 s45, s45, s41
	global_load_dword v120, v136, s[44:45] nt
	s_add_u32 s44, s44, s40
	s_addc_u32 s45, s45, s41
	global_load_dword v121, v136, s[44:45] nt
	s_cmp_eq_u64 s[36:37], 0
	s_cbranch_scc1 .Lcv_ng_a_5
	s_lshl_b32 s61, s61, 2
	s_add_u32 s44, s58, s61
	s_addc_u32 s45, s59, 0
	global_load_dword v122, v141, s[44:45] offset:0
	global_load_dword v123, v141, s[44:45] offset:32
	global_load_dword v124, v141, s[44:45] offset:64
	global_load_dword v125, v141, s[44:45] offset:96
	global_load_dword v126, v141, s[44:45] offset:128
	global_load_dword v127, v141, s[44:45] offset:160
	global_load_dword v128, v141, s[44:45] offset:192
	global_load_dword v129, v141, s[44:45] offset:224
.Lcv_ng_a_5:
	s_add_i32 s60, s60, 1
	s_add_i32 s30, s30, s9

; __device__ __forceinline__ void phase_convert(const Ctx& a, int l, LAS unsigned char* lds) {
;     ...
;         if (first < ntile) CV_LOAD(first);
;         for (int i = first; i < ntile; i += gridDim.x) {
;             const int kt = i / nnt, ntl = i % nnt, k0 = kt * 64, n0 = ntl * 64;
; #pragma unroll
;             for (int it = 0; it < 8; ++it) tile[((tid >> 6) + it * 8) * 65 + (tid & 63)] = pv[it];
;             __syncthreads();
;             if (i + (int)gridDim.x < ntile) CV_LOAD(i + gridDim.x);
.Lcv_top:
	v_pk_mul_f32 v[34:35], v[34:35], v[42:43]
	v_pk_mul_f32 v[36:37], v[36:37], v[44:45]
	v_pk_mul_f32 v[38:39], v[38:39], v[46:47]
	v_pk_mul_f32 v[40:41], v[40:41], v[48:49]
	v_cmp_gt_u32_e32 vcc, s50, v130
	v_cndmask_b32_e32 v34, 0, v34, vcc
	v_cndmask_b32_e32 v35, 0, v35, vcc
	v_cndmask_b32_e32 v36, 0, v36, vcc
	v_cndmask_b32_e32 v37, 0, v37, vcc
	v_cndmask_b32_e32 v38, 0, v38, vcc
	v_cndmask_b32_e32 v39, 0, v39, vcc
	v_cndmask_b32_e32 v40, 0, v40, vcc
	v_cndmask_b32_e32 v41, 0, v41, vcc
	ds_write_b32 v20, v34 offset:0
	ds_write_b32 v20, v35 offset:2080
	ds_write_b32 v20, v36 offset:4160
	ds_write_b32 v20, v37 offset:6240
	ds_write_b32 v20, v38 offset:8320
	ds_write_b32 v20, v39 offset:10400
	ds_write_b32 v20, v40 offset:12480
	ds_write_b32 v20, v41 offset:14560
	s_cmp_le_u32 s60, 1
	s_cbranch_scc1 .Lcv_wr_done
	v_pk_mul_f32 v[50:51], v[50:51], v[58:59]
	v_pk_mul_f32 v[52:53], v[52:53], v[60:61]
	v_pk_mul_f32 v[54:55], v[54:55], v[62:63]
	v_pk_mul_f32 v[56:57], v[56:57], v[64:65]
	v_cmp_gt_u32_e32 vcc, s50, v131
	v_cndmask_b32_e32 v50, 0, v50, vcc
	v_cndmask_b32_e32 v51, 0, v51, vcc
	v_cndmask_b32_e32 v52, 0, v52, vcc
	v_cndmask_b32_e32 v53, 0, v53, vcc
	v_cndmask_b32_e32 v54, 0, v54, vcc
	v_cndmask_b32_e32 v55, 0, v55, vcc
	v_cndmask_b32_e32 v56, 0, v56, vcc
	v_cndmask_b32_e32 v57, 0, v57, vcc
	ds_write_b32 v20, v50 offset:16640
	ds_write_b32 v20, v51 offset:18720
	ds_write_b32 v20, v52 offset:20800
	ds_write_b32 v20, v53 offset:22880
	ds_write_b32 v20, v54 offset:24960
	ds_write_b32 v20, v55 offset:27040
	ds_write_b32 v20, v56 offset:29120
	ds_write_b32 v20, v57 offset:31200
	s_cmp_le_u32 s60, 2
	s_cbranch_scc1 .Lcv_wr_done
	v_pk_mul_f32 v[66:67], v[66:67], v[74:75]
	v_pk_mul_f32 v[68:69], v[68:69], v[76:77]
	v_pk_mul_f32 v[70:71], v[70:71], v[78:79]
	v_pk_mul_f32 v[72:73], v[72:73], v[80:81]
	v_cmp_gt_u32_e32 vcc, s50, v132
	v_cndmask_b32_e32 v66, 0, v66, vcc
	v_cndmask_b32_e32 v67, 0, v67, vcc
	v_cndmask_b32_e32 v68, 0, v68, vcc
	v_cndmask_b32_e32 v69, 0, v69, vcc
	v_cndmask_b32_e32 v70, 0, v70, vcc
	v_cndmask_b32_e32 v71, 0, v71, vcc
	v_cndmask_b32_e32 v72, 0, v72, vcc
	v_cndmask_b32_e32 v73, 0, v73, vcc
	ds_write_b32 v20, v66 offset:33280
	ds_write_b32 v20, v67 offset:35360
	ds_write_b32 v20, v68 offset:37440
	ds_write_b32 v20, v69 offset:39520
	ds_write_b32 v20, v70 offset:41600
	ds_write_b32 v20, v71 offset:43680
	ds_write_b32 v20, v72 offset:45760
	ds_write_b32 v20, v73 offset:47840
	s_cmp_le_u32 s60, 3
	s_cbranch_scc1 .Lcv_wr_done
	v_pk_mul_f32 v[82:83], v[82:83], v[90:91]
	v_pk_mul_f32 v[84:85], v[84:85], v[92:93]
	v_pk_mul_f32 v[86:87], v[86:87], v[94:95]
	v_pk_mul_f32 v[88:89], v[88:89], v[96:97]
	v_cmp_gt_u32_e32 vcc, s50, v133
	v_cndmask_b32_e32 v82, 0, v82, vcc
	v_cndmask_b32_e32 v83, 0, v83, vcc
	v_cndmask_b32_e32 v84, 0, v84, vcc
	v_cndmask_b32_e32 v85, 0, v85, vcc
	v_cndmask_b32_e32 v86, 0, v86, vcc
	v_cndmask_b32_e32 v87, 0, v87, vcc
	v_cndmask_b32_e32 v88, 0, v88, vcc
	v_cndmask_b32_e32 v89, 0, v89, vcc
	ds_write_b32 v20, v82 offset:49920
	ds_write_b32 v20, v83 offset:52000
	ds_write_b32 v20, v84 offset:54080
	ds_write_b32 v20, v85 offset:56160
	ds_write_b32 v20, v86 offset:58240
	ds_write_b32 v20, v87 offset:60320
	ds_write_b32 v20, v88 offset:62400
	ds_write_b32 v20, v89 offset:64480
	s_cmp_le_u32 s60, 4
	s_cbranch_scc1 .Lcv_wr_done
	v_pk_mul_f32 v[98:99], v[98:99], v[106:107]
	v_pk_mul_f32 v[100:101], v[100:101], v[108:109]
	v_pk_mul_f32 v[102:103], v[102:103], v[110:111]
	v_pk_mul_f32 v[104:105], v[104:105], v[112:113]
	v_cmp_gt_u32_e32 vcc, s50, v134
	v_cndmask_b32_e32 v98, 0, v98, vcc
	v_cndmask_b32_e32 v99, 0, v99, vcc
	v_cndmask_b32_e32 v100, 0, v100, vcc
	v_cndmask_b32_e32 v101, 0, v101, vcc
	v_cndmask_b32_e32 v102, 0, v102, vcc
	v_cndmask_b32_e32 v103, 0, v103, vcc
	v_cndmask_b32_e32 v104, 0, v104, vcc
	v_cndmask_b32_e32 v105, 0, v105, vcc
	ds_write_b32 v32, v98 offset:0
	ds_write_b32 v32, v99 offset:2080
	ds_write_b32 v32, v100 offset:4160
	ds_write_b32 v32, v101 offset:6240
	ds_write_b32 v32, v102 offset:8320
	ds_write_b32 v32, v103 offset:10400
	ds_write_b32 v32, v104 offset:12480
	ds_write_b32 v32, v105 offset:14560
	s_cmp_le_u32 s60, 5
	s_cbranch_scc1 .Lcv_wr_done
	v_pk_mul_f32 v[114:115], v[114:115], v[122:123]
	v_pk_mul_f32 v[116:117], v[116:117], v[124:125]
	v_pk_mul_f32 v[118:119], v[118:119], v[126:127]
	v_pk_mul_f32 v[120:121], v[120:121], v[128:129]
	v_cmp_gt_u32_e32 vcc, s50, v135
	v_cndmask_b32_e32 v114, 0, v114, vcc
	v_cndmask_b32_e32 v115, 0, v115, vcc
	v_cndmask_b32_e32 v116, 0, v116, vcc
	v_cndmask_b32_e32 v117, 0, v117, vcc
	v_cndmask_b32_e32 v118, 0, v118, vcc
	v_cndmask_b32_e32 v119, 0, v119, vcc
	v_cndmask_b32_e32 v120, 0, v120, vcc
	v_cndmask_b32_e32 v121, 0, v121, vcc
	ds_write_b32 v32, v114 offset:16640
	ds_write_b32 v32, v115 offset:18720
	ds_write_b32 v32, v116 offset:20800
	ds_write_b32 v32, v117 offset:22880
	ds_write_b32 v32, v118 offset:24960
	ds_write_b32 v32, v119 offset:27040
	ds_write_b32 v32, v120 offset:29120
	ds_write_b32 v32, v121 offset:31200
.Lcv_wr_done:
	s_waitcnt lgkmcnt(0)
	s_barrier
	s_mov_b32 s47, s53
	s_mov_b32 s63, s60
	s_mul_i32 s26, s9, 6
	s_add_i32 s53, s53, s26
	s_mov_b32 s60, 0
	s_mov_b32 s30, s53
	s_cmp_ge_i32 s30, s52
	s_cbranch_scc1 .Lcv_isd_b
	s_mul_hi_u32 s26, s30, s54
	s_mul_i32 s55, s26, s51
	s_sub_i32 s55, s30, s55
	s_sub_i32 s61, s55, s51
	s_add_i32 s62, s26, 1
	s_cmp_ge_u32 s55, s51
	s_cselect_b32 s26, s62, s26
	s_cselect_b32 s55, s61, s55
	s_sub_i32 s61, s55, s51
	s_add_i32 s62, s26, 1
	s_cmp_ge_u32 s55, s51
	s_cselect_b32 s26, s62, s26
	s_cselect_b32 s55, s61, s55
	s_lshl_b32 s61, s26, 6
	s_lshl_b32 s62, s55, 6
	v_add_u32_e32 v130, s62, v1
	s_add_i32 s44, s50, -1
	v_min_u32_e32 v136, s44, v130
	v_add_u32_e32 v137, s61, v2
	v_mad_u32_u24 v136, v137, s0, v136
	v_lshlrev_b32_e32 v136, 2, v136
	s_mov_b64 s[44:45], s[56:57]
	global_load_dword v34, v136, s[44:45] nt
	s_add_u32 s44, s44, s40
	s_addc_u32 s45, s45, s41
	global_load_dword v35, v136, s[44:45] nt
	s_add_u32 s44, s44, s40
	s_addc_u32 s45, s45, s41
	global_load_dword v36, v136, s[44:45] nt
	s_add_u32 s44, s44, s40
	s_addc_u32 s45, s45, s41
	global_load_dword v37, v136, s[44:45] nt
	s_add_u32 s44, s44, s40
	s_addc_u32 s45, s45, s41
	global_load_dword v38, v136, s[44:45] nt
	s_add_u32 s44, s44, s40
	s_addc_u32 s45, s45, s41
	global_load_dword v39, v136, s[44:45] nt
	s_add_u32 s44, s44, s40
	s_addc_u32 s45, s45, s41
	global_load_dword v40, v136, s[44:45] nt
	s_add_u32 s44, s44, s40
	s_addc_u32 s45, s45, s41
	global_load_dword v41, v136, s[44:45] nt
	s_cmp_eq_u64 s[36:37], 0
	s_cbranch_scc1 .Lcv_ng_b_0
	s_lshl_b32 s61, s61, 2
	s_add_u32 s44, s58, s61
	s_addc_u32 s45, s59, 0
	global_load_dword v42, v141, s[44:45] offset:0
	global_load_dword v43, v141, s[44:45] offset:32
	global_load_dword v44, v141, s[44:45] offset:64
	global_load_dword v45, v141, s[44:45] offset:96
	global_load_dword v46, v141, s[44:45] offset:128
	global_load_dword v47, v141, s[44:45] offset:160
	global_load_dword v48, v141, s[44:45] offset:192
	global_load_dword v49, v141, s[44:45] offset:224

; __device__ __forceinline__ unsigned cvt_pk(float lo, float hi) { f32x2_t v = {lo, hi}; bf16x2_t b = __builtin_convertvector(v, bf16x2_t); return __builtin_bit_cast(unsigned, b); }
; __device__ __forceinline__ void phase_convert(const Ctx& a, int l, LAS unsigned char* lds) {
;     ...
;             {
;                 int nn = tid >> 3, kc = (tid & 7) * 8, n = n0 + nn, row = n;
;                 if (c.perm) { if (n < FF) row = (n / 128) * 256 + (n % 128); else { int jn = n - FF; row = (jn / 128) * 256 + 128 + (jn % 128); } }
;                 u32x4 w;
;                 w[0] = cvt_pk(tile[(kc + 0) * 65 + nn], tile[(kc + 1) * 65 + nn]);
;                 w[1] = cvt_pk(tile[(kc + 2) * 65 + nn], tile[(kc + 3) * 65 + nn]);
;                 w[2] = cvt_pk(tile[(kc + 4) * 65 + nn], tile[(kc + 5) * 65 + nn]);
;                 w[3] = cvt_pk(tile[(kc + 6) * 65 + nn], tile[(kc + 7) * 65 + nn]);
;                 *(u32x4*)(c.dst + (size_t)row * c.lddst + c.koff + k0 + kc) = w;
;             }
.Lcv_isd_b:
	s_mul_hi_u32 s26, s47, s54
	s_mul_i32 s55, s26, s51
	s_sub_i32 s55, s47, s55
	s_sub_i32 s61, s55, s51
	s_add_i32 s62, s26, 1
	s_cmp_ge_u32 s55, s51
	s_cselect_b32 s26, s62, s26
	s_cselect_b32 s55, s61, s55
	s_sub_i32 s61, s55, s51
	s_add_i32 s62, s26, 1
	s_cmp_ge_u32 s55, s51
	s_cselect_b32 s26, s62, s26
	s_cselect_b32 s55, s61, s55
	s_lshl_b32 s61, s26, 7
	s_lshl_b32 s62, s55, 6
	v_add_u32_e32 v138, s62, v11
	v_cmp_gt_u32_e32 vcc, 0xb00, v138
	v_subrev_u32_e32 v139, 0xb00, v138
	v_cndmask_b32_e32 v139, v139, v138, vcc
	v_lshrrev_b32_e32 v140, 7, v139
	v_and_b32_e32 v139, 0x7f, v139
	v_lshl_or_b32 v139, v140, 8, v139
	v_mov_b32_e32 v140, 0x80
	v_cndmask_b32_e32 v140, v140, v145, vcc
	v_or_b32_e32 v139, v139, v140
	v_cndmask_b32_e64 v138, v138, v139, s[42:43]
	v_mul_u32_u24_e32 v139, s12, v138
	v_lshl_add_u32 v139, v139, 1, v144
	s_add_u32 s44, s38, s61
	s_addc_u32 s45, s39, 0
	v_add_u32_e32 v142, 0x0, v18
	v_add_u32_e32 v143, 0x400, v18
	ds_read2_b32 v[24:25], v142 offset1:65
	ds_read2_b32 v[26:27], v142 offset0:130 offset1:195
	ds_read2_b32 v[28:29], v143 offset0:4 offset1:69
	ds_read2_b32 v[30:31], v143 offset0:134 offset1:199
	s_waitcnt lgkmcnt(0)
	v_cvt_pk_bf16_f32 v4, v24, v25
	v_cvt_pk_bf16_f32 v5, v26, v27
	v_cvt_pk_bf16_f32 v6, v28, v29
	v_cvt_pk_bf16_f32 v7, v30, v31
	global_store_dwordx4 v139, v[4:7], s[44:45]
	s_add_i32 s47, s47, s9
	s_cmp_le_u32 s63, 1
	s_cbranch_scc1 .Lcv_rd_done
	s_mul_hi_u32 s26, s47, s54
	s_mul_i32 s55, s26, s51
	s_sub_i32 s55, s47, s55
	s_sub_i32 s61, s55, s51
	s_add_i32 s62, s26, 1
	s_cmp_ge_u32 s55, s51
	s_cselect_b32 s26, s62, s26
	s_cselect_b32 s55, s61, s55
	s_sub_i32 s61, s55, s51
	s_add_i32 s62, s26, 1
	s_cmp_ge_u32 s55, s51
	s_cselect_b32 s26, s62, s26
	s_cselect_b32 s55, s61, s55
	s_lshl_b32 s61, s26, 7
	s_lshl_b32 s62, s55, 6
	v_add_u32_e32 v138, s62, v11
	v_cmp_gt_u32_e32 vcc, 0xb00, v138
	v_subrev_u32_e32 v139, 0xb00, v138
	v_cndmask_b32_e32 v139, v139, v138, vcc
	v_lshrrev_b32_e32 v140, 7, v139
	v_and_b32_e32 v139, 0x7f, v139
	v_lshl_or_b32 v139, v140, 8, v139
	v_mov_b32_e32 v140, 0x80
	v_cndmask_b32_e32 v140, v140, v145, vcc
	v_or_b32_e32 v139, v139, v140
	v_cndmask_b32_e64 v138, v138, v139, s[42:43]
	v_mul_u32_u24_e32 v139, s12, v138
	v_lshl_add_u32 v139, v139, 1, v144
	s_add_u32 s44, s38, s61
	s_addc_u32 s45, s39, 0
	v_add_u32_e32 v142, 0x4100, v18
	v_add_u32_e32 v143, 0x4500, v18
	ds_read2_b32 v[24:25], v142 offset1:65
	ds_read2_b32 v[26:27], v142 offset0:130 offset1:195
	ds_read2_b32 v[28:29], v143 offset0:4 offset1:69
	ds_read2_b32 v[30:31], v143 offset0:134 offset1:199
	s_waitcnt lgkmcnt(0)
	v_cvt_pk_bf16_f32 v12, v24, v25
	v_cvt_pk_bf16_f32 v13, v26, v27
	v_cvt_pk_bf16_f32 v14, v28, v29
	v_cvt_pk_bf16_f32 v15, v30, v31
	global_store_dwordx4 v139, v[12:15], s[44:45]
	s_add_i32 s47, s47, s9
	s_cmp_le_u32 s63, 2
	s_cbranch_scc1 .Lcv_rd_done
	s_mul_hi_u32 s26, s47, s54
	s_mul_i32 s55, s26, s51
	s_sub_i32 s55, s47, s55
	s_sub_i32 s61, s55, s51
	s_add_i32 s62, s26, 1
	s_cmp_ge_u32 s55, s51
	s_cselect_b32 s26, s62, s26
	s_cselect_b32 s55, s61, s55
	s_sub_i32 s61, s55, s51
	s_add_i32 s62, s26, 1
	s_cmp_ge_u32 s55, s51
	s_cselect_b32 s26, s62, s26
	s_cselect_b32 s55, s61, s55
	s_lshl_b32 s61, s26, 7
	s_lshl_b32 s62, s55, 6
	v_add_u32_e32 v138, s62, v11
	v_cmp_gt_u32_e32 vcc, 0xb00, v138
	v_subrev_u32_e32 v139, 0xb00, v138
	v_cndmask_b32_e32 v139, v139, v138, vcc
	v_lshrrev_b32_e32 v140, 7, v139
	v_and_b32_e32 v139, 0x7f, v139
	v_lshl_or_b32 v139, v140, 8, v139
	v_mov_b32_e32 v140, 0x80
	v_cndmask_b32_e32 v140, v140, v145, vcc
	v_or_b32_e32 v139, v139, v140
	v_cndmask_b32_e64 v138, v138, v139, s[42:43]
	v_mul_u32_u24_e32 v139, s12, v138
	v_lshl_add_u32 v139, v139, 1, v144
	s_add_u32 s44, s38, s61
	s_addc_u32 s45, s39, 0
	v_add_u32_e32 v142, 0x8200, v18
	v_add_u32_e32 v143, 0x8600, v18
	ds_read2_b32 v[24:25], v142 offset1:65
	ds_read2_b32 v[26:27], v142 offset0:130 offset1:195
	ds_read2_b32 v[28:29], v143 offset0:4 offset1:69
	ds_read2_b32 v[30:31], v143 offset0:134 offset1:199
	s_waitcnt lgkmcnt(0)
	v_cvt_pk_bf16_f32 v4, v24, v25
	v_cvt_pk_bf16_f32 v5, v26, v27
	v_cvt_pk_bf16_f32 v6, v28, v29
	v_cvt_pk_bf16_f32 v7, v30, v31
	global_store_dwordx4 v139, v[4:7], s[44:45]
	s_add_i32 s47, s47, s9
	s_cmp_le_u32 s63, 3
	s_cbranch_scc1 .Lcv_rd_done
; __device__ __forceinline__ unsigned cvt_pk(float lo, float hi) { f32x2_t v = {lo, hi}; bf16x2_t b = __builtin_convertvector(v, bf16x2_t); return __builtin_bit_cast(unsigned, b); }
; __device__ __forceinline__ void phase_convert(const Ctx& a, int l, LAS unsigned char* lds) {
;     ...
;             {
;                 int nn = tid >> 3, kc = (tid & 7) * 8, n = n0 + nn, row = n;
;                 if (c.perm) { if (n < FF) row = (n / 128) * 256 + (n % 128); else { int jn = n - FF; row = (jn / 128) * 256 + 128 + (jn % 128); } }
;                 u32x4 w;
;                 w[0] = cvt_pk(tile[(kc + 0) * 65 + nn], tile[(kc + 1) * 65 + nn]);
;                 w[1] = cvt_pk(tile[(kc + 2) * 65 + nn], tile[(kc + 3) * 65 + nn]);
;                 w[2] = cvt_pk(tile[(kc + 4) * 65 + nn], tile[(kc + 5) * 65 + nn]);
;                 w[3] = cvt_pk(tile[(kc + 6) * 65 + nn], tile[(kc + 7) * 65 + nn]);
;                 *(u32x4*)(c.dst + (size_t)row * c.lddst + c.koff + k0 + kc) = w;
;             }
;             __syncthreads();
	s_mul_hi_u32 s26, s47, s54
	s_mul_i32 s55, s26, s51
	s_sub_i32 s55, s47, s55
	s_sub_i32 s61, s55, s51
	s_add_i32 s62, s26, 1
	s_cmp_ge_u32 s55, s51
	s_cselect_b32 s26, s62, s26
	s_cselect_b32 s55, s61, s55
	s_sub_i32 s61, s55, s51
	s_add_i32 s62, s26, 1
	s_cmp_ge_u32 s55, s51
	s_cselect_b32 s26, s62, s26
	s_cselect_b32 s55, s61, s55
	s_lshl_b32 s61, s26, 7
	s_lshl_b32 s62, s55, 6
	v_add_u32_e32 v138, s62, v11
	v_cmp_gt_u32_e32 vcc, 0xb00, v138
	v_subrev_u32_e32 v139, 0xb00, v138
	v_cndmask_b32_e32 v139, v139, v138, vcc
	v_lshrrev_b32_e32 v140, 7, v139
	v_and_b32_e32 v139, 0x7f, v139
	v_lshl_or_b32 v139, v140, 8, v139
	v_mov_b32_e32 v140, 0x80
	v_cndmask_b32_e32 v140, v140, v145, vcc
	v_or_b32_e32 v139, v139, v140
	v_cndmask_b32_e64 v138, v138, v139, s[42:43]
	v_mul_u32_u24_e32 v139, s12, v138
	v_lshl_add_u32 v139, v139, 1, v144
	s_add_u32 s44, s38, s61
	s_addc_u32 s45, s39, 0
	v_add_u32_e32 v142, 0xc300, v18
	v_add_u32_e32 v143, 0xc700, v18
	ds_read2_b32 v[24:25], v142 offset1:65
	ds_read2_b32 v[26:27], v142 offset0:130 offset1:195
	ds_read2_b32 v[28:29], v143 offset0:4 offset1:69
	ds_read2_b32 v[30:31], v143 offset0:134 offset1:199
	s_waitcnt lgkmcnt(0)
	v_cvt_pk_bf16_f32 v12, v24, v25
	v_cvt_pk_bf16_f32 v13, v26, v27
	v_cvt_pk_bf16_f32 v14, v28, v29
	v_cvt_pk_bf16_f32 v15, v30, v31
	global_store_dwordx4 v139, v[12:15], s[44:45]
	s_add_i32 s47, s47, s9
	s_cmp_le_u32 s63, 4
	s_cbranch_scc1 .Lcv_rd_done
	s_mul_hi_u32 s26, s47, s54
	s_mul_i32 s55, s26, s51
	s_sub_i32 s55, s47, s55
	s_sub_i32 s61, s55, s51
	s_add_i32 s62, s26, 1
	s_cmp_ge_u32 s55, s51
	s_cselect_b32 s26, s62, s26
	s_cselect_b32 s55, s61, s55
	s_sub_i32 s61, s55, s51
	s_add_i32 s62, s26, 1
	s_cmp_ge_u32 s55, s51
	s_cselect_b32 s26, s62, s26
	s_cselect_b32 s55, s61, s55
	s_lshl_b32 s61, s26, 7
	s_lshl_b32 s62, s55, 6
	v_add_u32_e32 v138, s62, v11
	v_cmp_gt_u32_e32 vcc, 0xb00, v138
	v_subrev_u32_e32 v139, 0xb00, v138
	v_cndmask_b32_e32 v139, v139, v138, vcc
	v_lshrrev_b32_e32 v140, 7, v139
	v_and_b32_e32 v139, 0x7f, v139
	v_lshl_or_b32 v139, v140, 8, v139
	v_mov_b32_e32 v140, 0x80
	v_cndmask_b32_e32 v140, v140, v145, vcc
	v_or_b32_e32 v139, v139, v140
	v_cndmask_b32_e64 v138, v138, v139, s[42:43]
	v_mul_u32_u24_e32 v139, s12, v138
	v_lshl_add_u32 v139, v139, 1, v144
	s_add_u32 s44, s38, s61
	s_addc_u32 s45, s39, 0
	v_add_u32_e32 v142, 0x10400, v18
	v_add_u32_e32 v143, 0x10800, v18
	ds_read2_b32 v[24:25], v142 offset1:65
	ds_read2_b32 v[26:27], v142 offset0:130 offset1:195
	ds_read2_b32 v[28:29], v143 offset0:4 offset1:69
	ds_read2_b32 v[30:31], v143 offset0:134 offset1:199
	s_waitcnt lgkmcnt(0)
	v_cvt_pk_bf16_f32 v4, v24, v25
	v_cvt_pk_bf16_f32 v5, v26, v27
	v_cvt_pk_bf16_f32 v6, v28, v29
	v_cvt_pk_bf16_f32 v7, v30, v31
	global_store_dwordx4 v139, v[4:7], s[44:45]
	s_add_i32 s47, s47, s9
	s_cmp_le_u32 s63, 5
	s_cbranch_scc1 .Lcv_rd_done
	s_mul_hi_u32 s26, s47, s54
	s_mul_i32 s55, s26, s51
	s_sub_i32 s55, s47, s55
	s_sub_i32 s61, s55, s51
	s_add_i32 s62, s26, 1
	s_cmp_ge_u32 s55, s51
	s_cselect_b32 s26, s62, s26
	s_cselect_b32 s55, s61, s55
	s_sub_i32 s61, s55, s51
	s_add_i32 s62, s26, 1
	s_cmp_ge_u32 s55, s51
	s_cselect_b32 s26, s62, s26
	s_cselect_b32 s55, s61, s55
	s_lshl_b32 s61, s26, 7
	s_lshl_b32 s62, s55, 6
	v_add_u32_e32 v138, s62, v11
	v_cmp_gt_u32_e32 vcc, 0xb00, v138
	v_subrev_u32_e32 v139, 0xb00, v138
	v_cndmask_b32_e32 v139, v139, v138, vcc
	v_lshrrev_b32_e32 v140, 7, v139
	v_and_b32_e32 v139, 0x7f, v139
	v_lshl_or_b32 v139, v140, 8, v139
	v_mov_b32_e32 v140, 0x80
	v_cndmask_b32_e32 v140, v140, v145, vcc
	v_or_b32_e32 v139, v139, v140
	v_cndmask_b32_e64 v138, v138, v139, s[42:43]
	v_mul_u32_u24_e32 v139, s12, v138
	v_lshl_add_u32 v139, v139, 1, v144
	s_add_u32 s44, s38, s61
	s_addc_u32 s45, s39, 0
	v_add_u32_e32 v142, 0x14500, v18
	v_add_u32_e32 v143, 0x14900, v18
	ds_read2_b32 v[24:25], v142 offset1:65
	ds_read2_b32 v[26:27], v142 offset0:130 offset1:195
	ds_read2_b32 v[28:29], v143 offset0:4 offset1:69
	ds_read2_b32 v[30:31], v143 offset0:134 offset1:199
	s_waitcnt lgkmcnt(0)
	v_cvt_pk_bf16_f32 v12, v24, v25
	v_cvt_pk_bf16_f32 v13, v26, v27
	v_cvt_pk_bf16_f32 v14, v28, v29
	v_cvt_pk_bf16_f32 v15, v30, v31
	global_store_dwordx4 v139, v[12:15], s[44:45]
	s_add_i32 s47, s47, s9
.Lcv_rd_done:
	s_barrier
	s_cmp_eq_u32 s60, 0
	s_cbranch_scc1 .LBB0_693
	s_waitcnt vmcnt(0)
	s_branch .Lcv_top
